# prologue: nt loads for read-once weight/x streams (quantize pass, bf16 transposes, cast rows); colmax pass keeps default policy
# speedup vs baseline: 1.0139x; 1.0028x over previous
; #define GAS __attribute__((address_space(1)))
; #define LAS __attribute__((address_space(3)))
; __device__ __forceinline__ void transpose_item_q(const float* __restrict__ W, int K, int N, signed char* __restrict__ WQ, const float* __restrict__ gk, const unsigned* __restrict__ cmax, LAS float* scr, int item, int lane, int* csum = nullptr) {
;     const int nblk = N / 32, kb = item / nblk, nb = item - kb * nblk, k0 = 64 * kb, n0 = 32 * nb;
;     const int rr = lane >> 3, c4 = (lane & 7) * 4;
; #pragma unroll
;     for (int hb = 0; hb < 2; ++hb) {
;         f32x4 v[4];
; #pragma unroll
;         for (int i = 0; i < 4; ++i) v[i] = *(const GAS f32x4*)(W + (size_t)(k0 + 8 * (4 * hb + i) + rr) * N + n0 + c4);
; #pragma unroll
;         for (int i = 0; i < 4; ++i) { if (gk) v[i] = v[i] * gk[k0 + 8 * (4 * hb + i) + rr]; }
; #pragma unroll
;         for (int i = 0; i < 4; ++i) { LAS float* d = scr + (8 * (4 * hb + i) + rr) * 33 + c4; d[0] = v[i].x; d[1] = v[i].y; d[2] = v[i].z; d[3] = v[i].w; }
;         asm volatile("" ::: "memory");
;     }
.LBB0_31:
	s_abs_i32 s15, s86
	s_mul_hi_u32 s18, s15, s85
	s_mul_i32 s19, s18, s68
	s_sub_i32 s15, s15, s19
	s_ashr_i32 s14, s86, 31
	s_add_i32 s19, s18, 1
	s_sub_i32 s31, s15, s68
	s_cmp_ge_u32 s15, s68
	s_cselect_b32 s18, s19, s18
	s_cselect_b32 s15, s31, s15
	s_add_i32 s19, s18, 1
	s_cmp_ge_u32 s15, s68
	s_cselect_b32 s15, s19, s18
	s_xor_b32 s15, s15, s14
	s_sub_i32 s34, s15, s14
	s_lshl_b32 s31, s34, 6
	v_add_u32_e32 v30, s31, v32
	v_add_u32_e32 v10, 16, v30
	v_mad_u64_u32 v[2:3], s[48:49], v30, s2, 0
	v_ashrrev_i32_e32 v13, 31, v10
	v_mad_u64_u32 v[10:11], s[48:49], v10, s2, 0
	v_ashrrev_i32_e32 v31, 31, v30
	v_mov_b32_e32 v4, v3
	v_mov_b32_e32 v12, v11
	v_mad_u64_u32 v[4:5], s[48:49], v31, s2, v[4:5]
	v_mad_u64_u32 v[12:13], s[48:49], v13, s2, v[12:13]
	s_mul_i32 s14, s87, s34
	v_mov_b32_e32 v3, v4
	v_add_u32_e32 v4, 8, v30
	v_mov_b32_e32 v11, v12
	v_add_u32_e32 v12, 24, v30
	s_add_i32 s44, s25, s14
	v_add_u32_e32 v58, s44, v36
	v_ashrrev_i32_e32 v59, 31, v58
	v_lshl_add_u64 v[58:59], v[58:59], 2, s[64:65]
	global_load_dword v60, v[58:59], off
	global_load_dword v61, v[58:59], off offset:64
	v_ashrrev_i32_e32 v7, 31, v4
	v_mad_u64_u32 v[4:5], s[48:49], v4, s2, 0
	v_ashrrev_i32_e32 v15, 31, v12
	v_mad_u64_u32 v[12:13], s[48:49], v12, s2, 0
	s_sub_i32 s18, s44, 32
	v_mov_b32_e32 v6, v5
	v_mov_b32_e32 v14, v13
	s_ashr_i32 s19, s18, 31
	v_mad_u64_u32 v[6:7], s[48:49], v7, s2, v[6:7]
	v_mad_u64_u32 v[14:15], s[48:49], v15, s2, v[14:15]
	s_waitcnt lgkmcnt(0)
	v_lshl_add_u64 v[28:29], s[18:19], 2, v[18:19]
	v_mov_b32_e32 v5, v6
	v_mov_b32_e32 v13, v14
	v_lshl_add_u64 v[2:3], v[2:3], 2, v[28:29]
	v_lshl_add_u64 v[4:5], v[4:5], 2, v[28:29]
	v_lshl_add_u64 v[10:11], v[10:11], 2, v[28:29]
	v_lshl_add_u64 v[12:13], v[12:13], 2, v[28:29]
	global_load_dwordx4 v[6:9], v[2:3], off nt
	s_nop 0
	global_load_dwordx4 v[2:5], v[4:5], off nt
	s_nop 0
	global_load_dwordx4 v[14:17], v[10:11], off nt
	s_nop 0
	global_load_dwordx4 v[10:13], v[12:13], off nt
	v_cndmask_b32_e64 v26, 0, 1, s[36:37]
	v_cmp_ne_u32_e64 s[48:49], 1, v26
	s_andn2_b64 vcc, exec, s[36:37]
	v_lshl_add_u64 v[26:27], v[30:31], 2, s[88:89]
	s_cbranch_vccnz .LBB0_39
	global_load_dword v38, v[26:27], off
	global_load_dword v52, v[26:27], off offset:32
	global_load_dword v54, v[26:27], off offset:64
	global_load_dword v56, v[26:27], off offset:96
	s_waitcnt vmcnt(0)
	v_pk_mul_f32 v[8:9], v[8:9], v[38:39] op_sel_hi:[1,0]
	v_pk_mul_f32 v[6:7], v[6:7], v[38:39] op_sel_hi:[1,0]
	v_pk_mul_f32 v[4:5], v[4:5], v[52:53] op_sel_hi:[1,0]
	v_pk_mul_f32 v[2:3], v[2:3], v[52:53] op_sel_hi:[1,0]
	v_pk_mul_f32 v[16:17], v[16:17], v[54:55] op_sel_hi:[1,0]
	v_pk_mul_f32 v[14:15], v[14:15], v[54:55] op_sel_hi:[1,0]
	v_pk_mul_f32 v[12:13], v[12:13], v[56:57] op_sel_hi:[1,0]
	v_pk_mul_f32 v[10:11], v[10:11], v[56:57] op_sel_hi:[1,0]
.LBB0_39:
	s_waitcnt vmcnt(3)
	ds_write2_b32 v37, v6, v7 offset1:1
	ds_write2_b32 v37, v8, v9 offset0:2 offset1:3
	v_add_u32_e32 v6, 0x420, v37
	s_waitcnt vmcnt(2)
	ds_write2_b32 v6, v2, v3 offset1:1
	v_add_u32_e32 v2, 0x428, v37
	ds_write2_b32 v2, v4, v5 offset1:1
	v_add_u32_e32 v2, 0x840, v37
	s_waitcnt vmcnt(1)
	ds_write2_b32 v2, v14, v15 offset1:1
	v_add_u32_e32 v2, 0x848, v37
	ds_write2_b32 v2, v16, v17 offset1:1
	v_add_u32_e32 v2, 0xc60, v37
	s_waitcnt vmcnt(0)
	ds_write2_b32 v2, v10, v11 offset1:1
	v_add_u32_e32 v2, 0xc68, v37
	ds_write2_b32 v2, v12, v13 offset1:1
	v_add_u32_e32 v2, 32, v30
	v_add_u32_e32 v10, 48, v30
	v_ashrrev_i32_e32 v5, 31, v2
	v_mad_u64_u32 v[2:3], vcc, v2, s2, 0
	v_ashrrev_i32_e32 v13, 31, v10
	v_mad_u64_u32 v[10:11], vcc, v10, s2, 0
	v_mov_b32_e32 v4, v3
	v_mov_b32_e32 v12, v11
	v_mad_u64_u32 v[4:5], vcc, v5, s2, v[4:5]
	v_mad_u64_u32 v[12:13], vcc, v13, s2, v[12:13]
	v_mov_b32_e32 v3, v4
	v_add_u32_e32 v4, 40, v30
	v_mov_b32_e32 v11, v12
	v_add_u32_e32 v12, 56, v30
	v_ashrrev_i32_e32 v7, 31, v4
	v_mad_u64_u32 v[4:5], vcc, v4, s2, 0
	v_ashrrev_i32_e32 v15, 31, v12
	v_mad_u64_u32 v[12:13], vcc, v12, s2, 0
	v_mov_b32_e32 v6, v5
	v_mov_b32_e32 v14, v13
	v_mad_u64_u32 v[6:7], vcc, v7, s2, v[6:7]
	v_mad_u64_u32 v[14:15], vcc, v15, s2, v[14:15]
	v_mov_b32_e32 v5, v6
	v_mov_b32_e32 v13, v14
	v_lshl_add_u64 v[2:3], v[2:3], 2, v[28:29]
	v_lshl_add_u64 v[4:5], v[4:5], 2, v[28:29]
	v_lshl_add_u64 v[10:11], v[10:11], 2, v[28:29]
	v_lshl_add_u64 v[12:13], v[12:13], 2, v[28:29]
	global_load_dwordx4 v[6:9], v[2:3], off nt
	s_nop 0
	global_load_dwordx4 v[2:5], v[4:5], off nt
	s_nop 0
	global_load_dwordx4 v[14:17], v[10:11], off nt
	s_nop 0
	global_load_dwordx4 v[10:13], v[12:13], off nt
	s_and_b64 vcc, exec, s[48:49]
	s_cbranch_vccnz .LBB0_47
	global_load_dword v28, v[26:27], off offset:128
	global_load_dword v52, v[26:27], off offset:160
	global_load_dword v54, v[26:27], off offset:192
	global_load_dword v56, v[26:27], off offset:224
	s_waitcnt vmcnt(0)
	v_pk_mul_f32 v[8:9], v[8:9], v[28:29] op_sel_hi:[1,0]
	v_pk_mul_f32 v[6:7], v[6:7], v[28:29] op_sel_hi:[1,0]
	v_pk_mul_f32 v[4:5], v[4:5], v[52:53] op_sel_hi:[1,0]
	v_pk_mul_f32 v[2:3], v[2:3], v[52:53] op_sel_hi:[1,0]
	v_pk_mul_f32 v[16:17], v[16:17], v[54:55] op_sel_hi:[1,0]
	v_pk_mul_f32 v[14:15], v[14:15], v[54:55] op_sel_hi:[1,0]
	v_pk_mul_f32 v[12:13], v[12:13], v[56:57] op_sel_hi:[1,0]
	v_pk_mul_f32 v[10:11], v[10:11], v[56:57] op_sel_hi:[1,0]

; #define GAS __attribute__((address_space(1)))
; #define LAS __attribute__((address_space(3)))
; #define LDS_WAIT() asm volatile("s_waitcnt lgkmcnt(0)" ::: "memory")
; __device__ __forceinline__ unsigned pk2(float lo, float hi) { return f2bf(lo) | (f2bf(hi) << 16); }
; template <bool GSQ = false>
; __device__ __forceinline__ void transpose_item(const float* __restrict__ W, int K, int N, bf16* __restrict__ WT, const float* __restrict__ gk, LAS float* scr, int item, int lane) {
;     const int nblk = N / 32, kb = item / nblk, nb = item - kb * nblk, k0 = 64 * kb, n0 = 32 * nb;
;     const int rr = lane >> 3, c4 = (lane & 7) * 4;
; #pragma unroll
;     for (int hb = 0; hb < 2; ++hb) {
;         f32x4 v[4];
; #pragma unroll
;         for (int i = 0; i < 4; ++i) v[i] = *(const GAS f32x4*)(W + (size_t)(k0 + 8 * (4 * hb + i) + rr) * N + n0 + c4);
;         if (gk) {
; #pragma unroll
;             for (int i = 0; i < 4; ++i) { float g_ = gk[k0 + 8 * (4 * hb + i) + rr]; if (GSQ) { g_ *= (1.0f / 127.0f); g_ *= g_; } v[i] = v[i] * g_; } }
; #pragma unroll
;         for (int i = 0; i < 4; ++i) { LAS float* d = scr + (8 * (4 * hb + i) + rr) * 33 + c4; d[0] = v[i].x; d[1] = v[i].y; d[2] = v[i].z; d[3] = v[i].w; }
;         asm volatile("" ::: "memory");
;     }
;     LDS_WAIT(); asm volatile("" ::: "memory");
;     const int c = lane & 7;
; #pragma unroll
;     for (int j = 0; j < 4; ++j) { const int n = (lane >> 3) + 8 * j; const LAS float* s = scr + (8 * c) * 33 + n;
;         v4u o; o.x = pk2(s[0 * 33], s[1 * 33]); o.y = pk2(s[2 * 33], s[3 * 33]); o.z = pk2(s[4 * 33], s[5 * 33]); o.w = pk2(s[6 * 33], s[7 * 33]);
;         *(GAS v4u*)(WT + ((((size_t)(n0 >> 8) * (K / 64) + kb) * 256 + (n0 & 255) + n) * 64 + 8 * c)) = o; }
;     LDS_WAIT(); asm volatile("" ::: "memory");
.LBB0_64:
	s_load_dwordx2 s[14:15], s[10:11], 0x50
	s_cmpk_gt_u32 s25, 0x67ff
	s_cselect_b64 s[18:19], -1, 0
	s_and_b64 s[30:31], s[18:19], exec
	s_cselect_b32 s30, 0x4000000, 0
	s_waitcnt lgkmcnt(0)
	s_add_u32 s30, s14, s30
	s_addc_u32 s31, s15, 0
	s_and_b64 s[14:15], s[18:19], exec
	s_cselect_b32 s14, 0xffffe000, 0
	s_cselect_b32 s34, 0x2000000, 0
	s_add_i32 s14, s14, s25
	s_add_i32 s15, s14, 0xb800
	s_sext_i32_i16 s18, s15
	s_bfe_u32 s18, s18, 0x70018
	s_add_i32 s15, s15, s18
	s_sext_i32_i16 s15, s15
	s_lshr_b32 s18, s15, 7
	s_ashr_i32 s19, s15, 7
	s_and_b32 s15, s15, 0xffffff80
	s_sub_i32 s14, s14, s15
	s_add_i32 s38, s14, 0xffffb800
	s_lshl_b32 s36, s38, 5
	s_ashr_i32 s37, s36, 31
	s_lshl_b64 s[14:15], s[36:37], 2
	v_lshl_add_u32 v2, s19, 6, v18
	s_add_u32 s14, s30, s14
	s_addc_u32 s15, s31, s15
	v_ashrrev_i32_e32 v3, 31, v2
	v_lshl_add_u64 v[4:5], s[14:15], 0, v[66:67]
	v_lshlrev_b64 v[2:3], 14, v[2:3]
	v_lshl_add_u64 v[32:33], v[4:5], 0, v[2:3]
	s_mov_b32 s14, 0x20000
	v_add_co_u32_e32 v6, vcc, s14, v32
	s_mov_b32 s14, 0x40000
	s_nop 0
	v_addc_co_u32_e32 v7, vcc, 0, v33, vcc
	global_load_dwordx4 v[2:5], v[32:33], off nt
	s_nop 0
	global_load_dwordx4 v[6:9], v[6:7], off nt
	v_add_co_u32_e32 v10, vcc, s14, v32
	s_mov_b32 s14, 0x60000
	s_nop 0
	v_addc_co_u32_e32 v11, vcc, 0, v33, vcc
	global_load_dwordx4 v[10:13], v[10:11], off nt
	v_add_co_u32_e32 v14, vcc, s14, v32
	s_mov_b32 s14, 0x80000
	s_nop 0
	v_addc_co_u32_e32 v15, vcc, 0, v33, vcc
	global_load_dwordx4 v[14:17], v[14:15], off nt
	v_add_co_u32_e32 v34, vcc, s14, v32
	s_mov_b32 s14, 0xa0000
	s_nop 0
	v_addc_co_u32_e32 v35, vcc, 0, v33, vcc
	v_add_co_u32_e32 v36, vcc, s14, v32
	s_mov_b32 s14, 0xc0000
	s_nop 0
	v_addc_co_u32_e32 v37, vcc, 0, v33, vcc
	v_add_co_u32_e32 v54, vcc, s14, v32
	s_mov_b32 s14, 0xe0000
	s_nop 0
	v_addc_co_u32_e32 v55, vcc, 0, v33, vcc
	s_bfe_i64 s[18:19], s[18:19], 0x100000
	s_lshl_b64 s[18:19], s[18:19], 8
	s_waitcnt vmcnt(3)
	ds_write2_b32 v38, v2, v3 offset1:1
	ds_write2_b32 v38, v4, v5 offset0:2 offset1:3
	s_waitcnt vmcnt(2)
	ds_write2_b32 v48, v6, v7 offset1:1
	ds_write2_b32 v49, v8, v9 offset1:1
	s_waitcnt vmcnt(1)
	ds_write2_b32 v51, v10, v11 offset1:1
	ds_write2_b32 v52, v12, v13 offset1:1
	s_waitcnt vmcnt(0)
	ds_write2_b32 v53, v14, v15 offset1:1
	ds_write2_b32 v47, v16, v17 offset1:1
	global_load_dwordx4 v[4:7], v[34:35], off nt
	global_load_dwordx4 v[8:11], v[36:37], off nt
	global_load_dwordx4 v[12:15], v[54:55], off nt
	v_add_co_u32_e32 v2, vcc, s14, v32
	s_ashr_i32 s14, s38, 3
	s_nop 0
	v_addc_co_u32_e32 v3, vcc, 0, v33, vcc
	global_load_dwordx4 v[32:35], v[2:3], off nt
	s_ashr_i32 s15, s14, 31
	s_lshl_b64 s[14:15], s[14:15], 14
	s_add_u32 s14, s14, s18
	s_addc_u32 s19, s15, s19
	s_and_b32 s15, s36, 0xe0
	s_or_b32 s18, s14, s15
	v_lshl_add_u64 v[16:17], s[18:19], 0, v[18:19]
	v_lshl_add_u64 v[2:3], v[28:29], 0, s[34:35]
	v_lshl_add_u64 v[36:37], s[18:19], 0, v[22:23]
	v_lshl_add_u64 v[54:55], s[18:19], 0, v[24:25]
	v_lshlrev_b64 v[16:17], 7, v[16:17]
	v_lshlrev_b64 v[36:37], 7, v[36:37]
	v_lshlrev_b64 v[54:55], 7, v[54:55]
	v_lshl_add_u64 v[16:17], v[2:3], 0, v[16:17]
	v_lshl_add_u64 v[36:37], v[2:3], 0, v[36:37]
	v_lshl_add_u64 v[54:55], v[2:3], 0, v[54:55]
	s_waitcnt vmcnt(3)
	ds_write2_b32 v40, v4, v5 offset1:1
	ds_write2_b32 v41, v6, v7 offset1:1
	s_waitcnt vmcnt(2)
	ds_write2_b32 v42, v8, v9 offset1:1
	ds_write2_b32 v43, v10, v11 offset1:1
	s_waitcnt vmcnt(1)
	ds_write2_b32 v44, v12, v13 offset1:1
	ds_write2_b32 v45, v14, v15 offset1:1
	s_waitcnt vmcnt(0)
	ds_write2_b32 v46, v32, v33 offset1:1
	ds_write2_b32 v39, v34, v35 offset1:1
	s_waitcnt lgkmcnt(0)
	ds_read2_b32 v[4:5], v21 offset0:33 offset1:41
	ds_read2_b32 v[6:7], v21 offset1:8
	ds_read2_b32 v[8:9], v21 offset0:66 offset1:74
	ds_read2_b32 v[10:11], v21 offset0:99 offset1:107
	ds_read2_b32 v[12:13], v21 offset0:132 offset1:140
	ds_read2_b32 v[14:15], v21 offset0:165 offset1:173
	ds_read2_b32 v[32:33], v21 offset0:198 offset1:206
	ds_read2_b32 v[34:35], v21 offset0:231 offset1:239
	ds_read2_b32 v[56:57], v21 offset0:49 offset1:57
	ds_read2_b32 v[58:59], v21 offset0:16 offset1:24
	ds_read2_b32 v[60:61], v21 offset0:82 offset1:90
	ds_read2_b32 v[62:63], v21 offset0:115 offset1:123
	ds_read2_b32 v[64:65], v21 offset0:148 offset1:156
	ds_read2_b32 v[76:77], v21 offset0:181 offset1:189
	ds_read2_b32 v[78:79], v21 offset0:214 offset1:222
	ds_read2_b32 v[80:81], v21 offset0:247 offset1:255
	s_waitcnt lgkmcnt(14)
	v_bfe_u32 v82, v6, 16, 1
	v_bfe_u32 v85, v5, 16, 1
	s_waitcnt lgkmcnt(13)
	v_bfe_u32 v86, v8, 16, 1
	v_bfe_u32 v87, v9, 16, 1
	s_waitcnt lgkmcnt(12)
	v_bfe_u32 v88, v10, 16, 1
	v_bfe_u32 v89, v11, 16, 1
	s_waitcnt lgkmcnt(11)
	v_bfe_u32 v90, v12, 16, 1
	v_bfe_u32 v91, v13, 16, 1
	s_waitcnt lgkmcnt(10)
	v_bfe_u32 v92, v14, 16, 1
	v_bfe_u32 v93, v15, 16, 1
	s_waitcnt lgkmcnt(9)
	v_bfe_u32 v94, v32, 16, 1
	v_bfe_u32 v83, v7, 16, 1
	v_bfe_u32 v84, v4, 16, 1
	v_bfe_u32 v95, v33, 16, 1
	s_waitcnt lgkmcnt(8)
	v_bfe_u32 v96, v34, 16, 1
	v_bfe_u32 v97, v35, 16, 1
	s_waitcnt lgkmcnt(6)
	v_bfe_u32 v98, v58, 16, 1
	v_bfe_u32 v99, v59, 16, 1
	s_waitcnt lgkmcnt(5)
	v_bfe_u32 v102, v60, 16, 1
	s_waitcnt lgkmcnt(4)
	v_bfe_u32 v103, v62, 16, 1
	s_waitcnt lgkmcnt(3)
	v_bfe_u32 v104, v64, 16, 1
	s_waitcnt lgkmcnt(2)
	v_bfe_u32 v105, v76, 16, 1
	s_waitcnt lgkmcnt(1)
	v_bfe_u32 v106, v78, 16, 1
	v_add3_u32 v6, v6, v82, s42
	v_add3_u32 v82, v5, v85, s42
	v_add3_u32 v5, v8, v86, s42
	v_add3_u32 v8, v9, v87, s42
	v_add3_u32 v9, v10, v88, s42
	v_add3_u32 v10, v11, v89, s42
	v_add3_u32 v11, v12, v90, s42
	v_add3_u32 v12, v13, v91, s42
	v_add3_u32 v13, v14, v92, s42
	v_add3_u32 v14, v15, v93, s42
	v_add3_u32 v15, v32, v94, s42
	v_bfe_u32 v100, v56, 16, 1
	s_waitcnt lgkmcnt(0)
; #define GAS __attribute__((address_space(1)))
; #define LAS __attribute__((address_space(3)))
; #define LDS_WAIT() asm volatile("s_waitcnt lgkmcnt(0)" ::: "memory")
; __device__ __forceinline__ unsigned pk2(float lo, float hi) { return f2bf(lo) | (f2bf(hi) << 16); }
; template <bool GSQ = false>
; __device__ __forceinline__ void transpose_item(const float* __restrict__ W, int K, int N, bf16* __restrict__ WT, const float* __restrict__ gk, LAS float* scr, int item, int lane) {
;     const int nblk = N / 32, kb = item / nblk, nb = item - kb * nblk, k0 = 64 * kb, n0 = 32 * nb;
;     const int rr = lane >> 3, c4 = (lane & 7) * 4;
; #pragma unroll
;     for (int hb = 0; hb < 2; ++hb) {
;         f32x4 v[4];
; #pragma unroll
;         for (int i = 0; i < 4; ++i) v[i] = *(const GAS f32x4*)(W + (size_t)(k0 + 8 * (4 * hb + i) + rr) * N + n0 + c4);
;         if (gk) {
; #pragma unroll
;             for (int i = 0; i < 4; ++i) { float g_ = gk[k0 + 8 * (4 * hb + i) + rr]; if (GSQ) { g_ *= (1.0f / 127.0f); g_ *= g_; } v[i] = v[i] * g_; } }
; #pragma unroll
;         for (int i = 0; i < 4; ++i) { LAS float* d = scr + (8 * (4 * hb + i) + rr) * 33 + c4; d[0] = v[i].x; d[1] = v[i].y; d[2] = v[i].z; d[3] = v[i].w; }
;         asm volatile("" ::: "memory");
;     }
;     LDS_WAIT(); asm volatile("" ::: "memory");
;     const int c = lane & 7;
; #pragma unroll
;     for (int j = 0; j < 4; ++j) { const int n = (lane >> 3) + 8 * j; const LAS float* s = scr + (8 * c) * 33 + n;
;         v4u o; o.x = pk2(s[0 * 33], s[1 * 33]); o.y = pk2(s[2 * 33], s[3 * 33]); o.z = pk2(s[4 * 33], s[5 * 33]); o.w = pk2(s[6 * 33], s[7 * 33]);
;         *(GAS v4u*)(WT + ((((size_t)(n0 >> 8) * (K / 64) + kb) * 256 + (n0 & 255) + n) * 64 + 8 * c)) = o; }
;     LDS_WAIT(); asm volatile("" ::: "memory");
; }
	v_bfe_u32 v107, v80, 16, 1
	v_add3_u32 v7, v7, v83, s42
	v_add3_u32 v4, v4, v84, s42
	v_add3_u32 v32, v33, v95, s42
	v_add3_u32 v33, v34, v96, s42
	v_add3_u32 v34, v35, v97, s42
	v_add3_u32 v35, v58, v98, s42
	v_add3_u32 v58, v59, v99, s42
	v_add3_u32 v59, v60, v102, s42
	v_add3_u32 v60, v62, v103, s42
	v_add3_u32 v62, v64, v104, s42
	v_add3_u32 v64, v76, v105, s42
	v_add3_u32 v76, v78, v106, s42
	v_lshrrev_b32_e32 v6, 16, v6
	v_lshrrev_b32_e32 v5, 16, v5
	v_lshrrev_b32_e32 v11, 16, v11
	v_lshrrev_b32_e32 v15, 16, v15
	v_add3_u32 v56, v56, v100, s42
	v_add3_u32 v78, v80, v107, s42
	v_lshrrev_b32_e32 v80, 16, v7
	v_lshrrev_b32_e32 v83, 16, v8
	v_lshrrev_b32_e32 v12, 16, v12
	v_lshrrev_b32_e32 v32, 16, v32
	v_lshrrev_b32_e32 v35, 16, v35
	v_lshrrev_b32_e32 v59, 16, v59
	v_lshrrev_b32_e32 v62, 16, v62
	v_lshrrev_b32_e32 v76, 16, v76
	v_and_or_b32 v4, v4, s26, v6
	v_and_or_b32 v5, v9, s26, v5
	v_and_or_b32 v6, v13, s26, v11
	v_and_or_b32 v7, v33, s26, v15
	v_and_or_b32 v8, v82, s26, v80
	v_and_or_b32 v9, v10, s26, v83
	v_and_or_b32 v10, v14, s26, v12
	v_and_or_b32 v11, v34, s26, v32
	v_and_or_b32 v12, v56, s26, v35
	v_and_or_b32 v13, v60, s26, v59
	v_and_or_b32 v14, v64, s26, v62
	v_and_or_b32 v15, v78, s26, v76
	global_store_dwordx4 v[16:17], v[4:7], off
	global_store_dwordx4 v[36:37], v[8:11], off
	global_store_dwordx4 v[54:55], v[12:15], off
	v_bfe_u32 v4, v61, 16, 1
	v_add3_u32 v4, v61, v4, s42
	v_bfe_u32 v5, v63, 16, 1
	v_lshrrev_b32_e32 v4, 16, v4
	v_add3_u32 v5, v63, v5, s42
	v_and_or_b32 v33, v5, s26, v4
	v_bfe_u32 v4, v65, 16, 1
	v_add3_u32 v4, v65, v4, s42
	v_bfe_u32 v5, v77, 16, 1
	v_lshrrev_b32_e32 v4, 16, v4
	v_add3_u32 v5, v77, v5, s42
	v_and_or_b32 v34, v5, s26, v4
	v_bfe_u32 v4, v79, 16, 1
	v_add3_u32 v4, v79, v4, s42
	v_bfe_u32 v5, v81, 16, 1
	v_lshrrev_b32_e32 v4, 16, v4
	v_add3_u32 v5, v81, v5, s42
	v_bfe_u32 v101, v57, 16, 1
	v_and_or_b32 v35, v5, s26, v4
	v_lshl_add_u64 v[4:5], s[18:19], 0, v[26:27]
	v_add3_u32 v57, v57, v101, s42
	v_lshrrev_b32_e32 v58, 16, v58
	v_lshlrev_b64 v[4:5], 7, v[4:5]
	v_and_or_b32 v32, v57, s26, v58
	v_lshl_add_u64 v[2:3], v[2:3], 0, v[4:5]
	global_store_dwordx4 v[2:3], v[32:35], off
	s_waitcnt lgkmcnt(0)
	s_cbranch_execnz .LBB0_61
.LBB0_65:
	s_mul_hi_i32 s14, s25, 0x38e38e39
	s_lshr_b32 s15, s14, 31
	s_ashr_i32 s14, s14, 6
	s_load_dwordx4 s[44:47], s[10:11], 0x10
	s_add_i32 s36, s14, s15
	s_mul_i32 s14, s36, 0xffffdc00
	s_add_i32 s18, s2, s14
	s_ashr_i32 s19, s18, 31
	s_lshl_b64 s[14:15], s[18:19], 2
	s_waitcnt lgkmcnt(0)
	s_add_u32 s14, s46, s14
	v_lshl_add_u32 v32, s36, 6, v18
	s_addc_u32 s15, s47, s15
	v_lshl_add_u64 v[36:37], s[14:15], 0, v[66:67]
	v_add_u32_e32 v4, 8, v32
	v_add_u32_e32 v10, 16, v32
	v_add_u32_e32 v12, 24, v32
	v_mad_i64_i32 v[2:3], s[14:15], v32, s27, v[36:37]
	v_mad_i64_i32 v[4:5], s[14:15], v4, s27, v[36:37]
	v_mad_i64_i32 v[10:11], s[14:15], v10, s27, v[36:37]
	v_mad_i64_i32 v[12:13], s[14:15], v12, s27, v[36:37]
	global_load_dwordx4 v[6:9], v[2:3], off nt
	s_nop 0
	global_load_dwordx4 v[2:5], v[4:5], off nt
	s_nop 0
	global_load_dwordx4 v[14:17], v[10:11], off nt
	s_nop 0
	global_load_dwordx4 v[10:13], v[12:13], off nt
	s_cmp_lg_u64 s[44:45], 0
	v_ashrrev_i32_e32 v33, 31, v32
	s_cselect_b64 s[38:39], -1, 0
	s_cmp_eq_u64 s[44:45], 0
	v_lshl_add_u64 v[34:35], v[32:33], 2, s[44:45]
	s_cbranch_scc1 .LBB0_67
	global_load_dword v54, v[34:35], off
	global_load_dword v56, v[34:35], off offset:32
	global_load_dword v58, v[34:35], off offset:64
	global_load_dword v60, v[34:35], off offset:96
	s_waitcnt vmcnt(3)
	v_pk_mul_f32 v[8:9], v[8:9], v[54:55] op_sel_hi:[1,0]
	v_pk_mul_f32 v[6:7], v[6:7], v[54:55] op_sel_hi:[1,0]
	s_waitcnt vmcnt(2)
	v_pk_mul_f32 v[4:5], v[4:5], v[56:57] op_sel_hi:[1,0]
	v_pk_mul_f32 v[2:3], v[2:3], v[56:57] op_sel_hi:[1,0]
	s_waitcnt vmcnt(1)
	v_pk_mul_f32 v[16:17], v[16:17], v[58:59] op_sel_hi:[1,0]
	v_pk_mul_f32 v[14:15], v[14:15], v[58:59] op_sel_hi:[1,0]
	s_waitcnt vmcnt(0)
	v_pk_mul_f32 v[12:13], v[12:13], v[60:61] op_sel_hi:[1,0]
	v_pk_mul_f32 v[10:11], v[10:11], v[60:61] op_sel_hi:[1,0]
.LBB0_67:
	s_waitcnt vmcnt(3)
	ds_write2_b32 v38, v6, v7 offset1:1
	ds_write2_b32 v38, v8, v9 offset0:2 offset1:3
	s_waitcnt vmcnt(2)
	ds_write2_b32 v48, v2, v3 offset1:1
	ds_write2_b32 v49, v4, v5 offset1:1
	s_waitcnt vmcnt(1)
	ds_write2_b32 v51, v14, v15 offset1:1
	ds_write2_b32 v52, v16, v17 offset1:1
	s_waitcnt vmcnt(0)
	ds_write2_b32 v53, v10, v11 offset1:1
	ds_write2_b32 v47, v12, v13 offset1:1
	v_add_u32_e32 v2, 32, v32
	v_add_u32_e32 v4, 40, v32
	v_add_u32_e32 v10, 48, v32
	v_add_u32_e32 v12, 56, v32
	v_mad_i64_i32 v[2:3], s[14:15], v2, s27, v[36:37]
	v_mad_i64_i32 v[4:5], s[14:15], v4, s27, v[36:37]
	v_mad_i64_i32 v[10:11], s[14:15], v10, s27, v[36:37]
	v_mad_i64_i32 v[12:13], s[14:15], v12, s27, v[36:37]
	global_load_dwordx4 v[6:9], v[2:3], off nt
	s_nop 0
	global_load_dwordx4 v[2:5], v[4:5], off nt
	s_nop 0
	global_load_dwordx4 v[14:17], v[10:11], off nt
	s_nop 0
	global_load_dwordx4 v[10:13], v[12:13], off nt
	s_andn2_b64 vcc, exec, s[38:39]
	s_cbranch_vccnz .LBB0_60
	global_load_dword v32, v[34:35], off offset:128
	global_load_dword v36, v[34:35], off offset:160
	global_load_dword v48, v[34:35], off offset:192
	s_nop 0
	global_load_dword v34, v[34:35], off offset:224
	s_waitcnt vmcnt(3)
	v_pk_mul_f32 v[8:9], v[8:9], v[32:33] op_sel_hi:[1,0]
	v_pk_mul_f32 v[6:7], v[6:7], v[32:33] op_sel_hi:[1,0]
	s_waitcnt vmcnt(2)
	v_pk_mul_f32 v[4:5], v[4:5], v[36:37] op_sel_hi:[1,0]
	v_pk_mul_f32 v[2:3], v[2:3], v[36:37] op_sel_hi:[1,0]
	s_waitcnt vmcnt(1)
	v_pk_mul_f32 v[16:17], v[16:17], v[48:49] op_sel_hi:[1,0]
	v_pk_mul_f32 v[14:15], v[14:15], v[48:49] op_sel_hi:[1,0]
	s_waitcnt vmcnt(0)
	v_pk_mul_f32 v[12:13], v[12:13], v[34:35] op_sel_hi:[1,0]
	v_pk_mul_f32 v[10:11], v[10:11], v[34:35] op_sel_hi:[1,0]
	s_branch .LBB0_60

; #define GAS __attribute__((address_space(1)))
; __device__ __forceinline__ unsigned pk2(float lo, float hi) { return f2bf(lo) | (f2bf(hi) << 16); }
; __device__ __forceinline__ float dot4(f32x4 a) { return (a.x * a.x + a.y * a.y) + (a.z * a.z + a.w * a.w); }
; template <bool QUANT>
; __device__ __forceinline__ void cast_row(const float* __restrict__ xrow, bf16* __restrict__ xbrow, float* rs_out, int lane, signed char* xqrow = nullptr, float* rf_out = nullptr) {
;     f32x4 x[8][2]; float s = 0.f, am = 0.f;
; #pragma unroll
;     for (int j = 0; j < 8; ++j) { x[j][0] = *(const GAS f32x4*)(xrow + 8 * lane + 512 * j); x[j][1] = *(const GAS f32x4*)(xrow + 8 * lane + 512 * j + 4); }
; #pragma unroll
;     for (int j = 0; j < 8; ++j) { s += dot4(x[j][0]) + dot4(x[j][1]);
;         if (QUANT) {
; #pragma unroll
;             for (int e = 0; e < 4; ++e) am = fmaxf(am, fmaxf(fabsf(x[j][0][e]), fabsf(x[j][1][e]))); }
;         else { v4u w; w.x = pk2(x[j][0].x, x[j][0].y); w.y = pk2(x[j][0].z, x[j][0].w); w.z = pk2(x[j][1].x, x[j][1].y); w.w = pk2(x[j][1].z, x[j][1].w);
;             *(GAS v4u*)(xbrow + 8 * lane + 512 * j) = w; } }
;     const float tot = wave_sum(s, lane); const float rsn = 1.0f / sqrtf(tot * (1.0f / DM) + EPS);
;     if (lane == 0) *rs_out = rsn;
.LBB0_80:
	s_movk_i32 s14, 0xc7f0
	s_mov_b32 s15, -1
	s_waitcnt lgkmcnt(0)
	v_lshl_add_u64 v[2:3], v[44:45], 0, s[14:15]
	s_movk_i32 s14, 0xcff0
	s_mov_b32 s15, -1
	global_load_dwordx4 v[58:61], v[2:3], off offset:16 nt
	v_lshl_add_u64 v[2:3], v[44:45], 0, s[14:15]
	global_load_dwordx4 v[34:37], v[2:3], off offset:16 nt
	v_add_co_u32_e32 v2, vcc, 0xffffd000, v44
	s_movk_i32 s14, 0xd7f0
	s_nop 0
	v_addc_co_u32_e32 v3, vcc, -1, v45, vcc
	global_load_dwordx4 v[62:65], v[2:3], off offset:-2064 nt
	global_load_dwordx4 v[38:41], v[2:3], off offset:-16 nt
	s_mov_b32 s15, -1
	v_lshl_add_u64 v[46:47], v[44:45], 0, s[14:15]
	s_movk_i32 s14, 0xdff0
	s_mov_b32 s15, -1
	v_lshl_add_u64 v[84:85], v[44:45], 0, s[14:15]
	s_movk_i32 s14, 0xe7f0
	s_mov_b32 s15, -1
	v_lshl_add_u64 v[18:19], v[44:45], 0, s[14:15]
	s_movk_i32 s14, 0xf000
	v_add_co_u32_e32 v22, vcc, s14, v44
	s_movk_i32 s14, 0xe000
	s_nop 0
	v_addc_co_u32_e32 v23, vcc, -1, v45, vcc
	v_add_co_u32_e32 v88, vcc, s14, v44
	global_load_dwordx4 v[10:13], v[44:45], off offset:-2048 nt
	global_load_dwordx4 v[14:17], v[44:45], off offset:-2064 nt
	global_load_dwordx4 v[2:5], v[44:45], off nt
	global_load_dwordx4 v[6:9], v[44:45], off offset:-16 nt
	global_load_dwordx4 v[26:29], v[18:19], off offset:16 nt
	global_load_dwordx4 v[30:33], v[22:23], off offset:-2064 nt
	s_nop 0
	global_load_dwordx4 v[18:21], v[44:45], off offset:-4096 nt
	s_nop 0
	global_load_dwordx4 v[22:25], v[22:23], off offset:-16 nt
	v_addc_co_u32_e32 v89, vcc, -1, v45, vcc
	global_load_dwordx4 v[76:79], v[46:47], off offset:16 nt
	global_load_dwordx4 v[80:83], v[88:89], off offset:-2064 nt
	v_lshl_add_u64 v[86:87], s[12:13], 0, v[42:43]
	s_mov_b32 s14, 0x2d200000
	v_add_co_u32_e64 v48, s[48:49], s14, v86
	s_mov_b32 s14, 0x2d201000
	v_add_co_u32_e32 v46, vcc, s14, v86
	v_addc_co_u32_e64 v49, s[48:49], 0, v87, s[48:49]
	s_nop 0
	v_addc_co_u32_e32 v47, vcc, 0, v87, vcc
	global_load_dwordx4 v[84:87], v[84:85], off offset:16 nt
	s_nop 0
	global_load_dwordx4 v[88:91], v[88:89], off offset:-16 nt
	s_waitcnt vmcnt(15)
	v_mul_f32_e32 v57, v59, v59
	v_mul_f32_e32 v66, v61, v61
	v_and_b32_sdwa v92, v60, v117 dst_sel:DWORD dst_unused:UNUSED_PAD src0_sel:WORD_1 src1_sel:DWORD
	v_and_b32_sdwa v93, v58, v117 dst_sel:DWORD dst_unused:UNUSED_PAD src0_sel:WORD_1 src1_sel:DWORD
	v_and_b32_sdwa v94, v61, v117 dst_sel:DWORD dst_unused:UNUSED_PAD src0_sel:WORD_1 src1_sel:DWORD
	v_and_b32_sdwa v95, v59, v117 dst_sel:DWORD dst_unused:UNUSED_PAD src0_sel:WORD_1 src1_sel:DWORD
	v_fmac_f32_e32 v57, v58, v58
	v_fmac_f32_e32 v66, v60, v60
	v_add3_u32 v58, v58, v93, s42
	v_add3_u32 v60, v60, v92, s42
	v_add3_u32 v61, v61, v94, s42
	v_add3_u32 v59, v59, v95, s42
	s_waitcnt vmcnt(13)
	v_mul_f32_e32 v92, v63, v63
	v_mul_f32_e32 v93, v65, v65
	v_and_b32_sdwa v98, v65, v117 dst_sel:DWORD dst_unused:UNUSED_PAD src0_sel:WORD_1 src1_sel:DWORD
	v_and_b32_sdwa v99, v63, v117 dst_sel:DWORD dst_unused:UNUSED_PAD src0_sel:WORD_1 src1_sel:DWORD
	v_and_b32_sdwa v94, v64, v117 dst_sel:DWORD dst_unused:UNUSED_PAD src0_sel:WORD_1 src1_sel:DWORD
	v_and_b32_sdwa v95, v62, v117 dst_sel:DWORD dst_unused:UNUSED_PAD src0_sel:WORD_1 src1_sel:DWORD
	v_and_b32_e32 v61, 0xffff0000, v61
	v_and_b32_e32 v59, 0xffff0000, v59
	v_fmac_f32_e32 v92, v62, v62
	v_fmac_f32_e32 v93, v64, v64
	v_add3_u32 v65, v65, v98, s42
	v_add3_u32 v63, v63, v99, s42
	v_mul_f32_e32 v96, v35, v35
	v_mul_f32_e32 v97, v37, v37
	s_waitcnt vmcnt(12)
	v_mul_f32_e32 v100, v39, v39
	v_mul_f32_e32 v101, v41, v41
	v_add_f32_e32 v57, v57, v66
	v_add3_u32 v62, v62, v95, s42
	v_add3_u32 v64, v64, v94, s42
	v_or_b32_sdwa v61, v61, v60 dst_sel:DWORD dst_unused:UNUSED_PAD src0_sel:DWORD src1_sel:WORD_1
	v_or_b32_sdwa v60, v59, v58 dst_sel:DWORD dst_unused:UNUSED_PAD src0_sel:DWORD src1_sel:WORD_1
	v_add_f32_e32 v58, v92, v93
	v_and_b32_e32 v59, 0xffff0000, v65
	v_and_b32_e32 v63, 0xffff0000, v63
	v_fmac_f32_e32 v96, v34, v34
	v_fmac_f32_e32 v100, v38, v38
	v_fmac_f32_e32 v101, v40, v40
	v_add_f32_e32 v57, v58, v57
	v_or_b32_sdwa v59, v59, v64 dst_sel:DWORD dst_unused:UNUSED_PAD src0_sel:DWORD src1_sel:WORD_1
	v_or_b32_sdwa v58, v63, v62 dst_sel:DWORD dst_unused:UNUSED_PAD src0_sel:DWORD src1_sel:WORD_1
	v_fmac_f32_e32 v97, v36, v36
	v_add_f32_e32 v65, v100, v101
	global_store_dwordx4 v[46:47], v[58:61], off offset:-4096
	s_nop 1
	v_add_f32_e32 v58, v96, v97
	v_add_f32_e32 v58, v65, v58
	v_add_f32_e32 v57, v57, v58
	v_and_b32_sdwa v58, v40, v117 dst_sel:DWORD dst_unused:UNUSED_PAD src0_sel:WORD_1 src1_sel:DWORD
	v_and_b32_sdwa v59, v38, v117 dst_sel:DWORD dst_unused:UNUSED_PAD src0_sel:WORD_1 src1_sel:DWORD
	v_add3_u32 v40, v40, v58, s42
	v_and_b32_sdwa v58, v41, v117 dst_sel:DWORD dst_unused:UNUSED_PAD src0_sel:WORD_1 src1_sel:DWORD
	v_add3_u32 v38, v38, v59, s42
	v_and_b32_sdwa v59, v39, v117 dst_sel:DWORD dst_unused:UNUSED_PAD src0_sel:WORD_1 src1_sel:DWORD
	v_add3_u32 v41, v41, v58, s42
	v_add3_u32 v39, v39, v59, s42
	v_and_b32_e32 v41, 0xffff0000, v41
	v_and_b32_e32 v58, 0xffff0000, v39
	v_or_b32_sdwa v39, v41, v40 dst_sel:DWORD dst_unused:UNUSED_PAD src0_sel:DWORD src1_sel:WORD_1
	v_and_b32_sdwa v41, v34, v117 dst_sel:DWORD dst_unused:UNUSED_PAD src0_sel:WORD_1 src1_sel:DWORD
	v_add3_u32 v34, v34, v41, s42
	v_and_b32_sdwa v41, v35, v117 dst_sel:DWORD dst_unused:UNUSED_PAD src0_sel:WORD_1 src1_sel:DWORD
	v_and_b32_sdwa v40, v36, v117 dst_sel:DWORD dst_unused:UNUSED_PAD src0_sel:WORD_1 src1_sel:DWORD
	v_add3_u32 v35, v35, v41, s42
	v_add3_u32 v36, v36, v40, s42
	v_and_b32_sdwa v40, v37, v117 dst_sel:DWORD dst_unused:UNUSED_PAD src0_sel:WORD_1 src1_sel:DWORD
	v_and_b32_e32 v35, 0xffff0000, v35
	v_add3_u32 v37, v37, v40, s42
	v_or_b32_sdwa v40, v35, v34 dst_sel:DWORD dst_unused:UNUSED_PAD src0_sel:DWORD src1_sel:WORD_1
	s_waitcnt vmcnt(3)
; #define GAS __attribute__((address_space(1)))
; __device__ __forceinline__ unsigned pk2(float lo, float hi) { return f2bf(lo) | (f2bf(hi) << 16); }
; __device__ __forceinline__ float dot4(f32x4 a) { return (a.x * a.x + a.y * a.y) + (a.z * a.z + a.w * a.w); }
; template <bool QUANT>
; __device__ __forceinline__ void cast_row(const float* __restrict__ xrow, bf16* __restrict__ xbrow, float* rs_out, int lane, signed char* xqrow = nullptr, float* rf_out = nullptr) {
;     ...
;     for (int j = 0; j < 8; ++j) { s += dot4(x[j][0]) + dot4(x[j][1]);
;         if (QUANT) {
; #pragma unroll
;             for (int e = 0; e < 4; ++e) am = fmaxf(am, fmaxf(fabsf(x[j][0][e]), fabsf(x[j][1][e]))); }
;         else { v4u w; w.x = pk2(x[j][0].x, x[j][0].y); w.y = pk2(x[j][0].z, x[j][0].w); w.z = pk2(x[j][1].x, x[j][1].y); w.w = pk2(x[j][1].z, x[j][1].w);
;             *(GAS v4u*)(xbrow + 8 * lane + 512 * j) = w; } }
	v_mul_f32_e32 v34, v81, v81
	v_mul_f32_e32 v35, v83, v83
	v_and_b32_e32 v37, 0xffff0000, v37
	v_fmac_f32_e32 v34, v80, v80
	v_fmac_f32_e32 v35, v82, v82
	v_or_b32_sdwa v41, v37, v36 dst_sel:DWORD dst_unused:UNUSED_PAD src0_sel:DWORD src1_sel:WORD_1
	v_add_f32_e32 v34, v34, v35
	v_mul_f32_e32 v35, v77, v77
	v_mul_f32_e32 v36, v79, v79
	v_fmac_f32_e32 v35, v76, v76
	v_fmac_f32_e32 v36, v78, v78
	v_add_f32_e32 v35, v35, v36
	v_add_f32_e32 v34, v34, v35
	v_and_b32_sdwa v35, v80, v117 dst_sel:DWORD dst_unused:UNUSED_PAD src0_sel:WORD_1 src1_sel:DWORD
	v_or_b32_sdwa v38, v58, v38 dst_sel:DWORD dst_unused:UNUSED_PAD src0_sel:DWORD src1_sel:WORD_1
	v_add3_u32 v36, v80, v35, s42
	v_and_b32_sdwa v35, v83, v117 dst_sel:DWORD dst_unused:UNUSED_PAD src0_sel:WORD_1 src1_sel:DWORD
	v_and_b32_sdwa v37, v81, v117 dst_sel:DWORD dst_unused:UNUSED_PAD src0_sel:WORD_1 src1_sel:DWORD
	global_store_dwordx4 v[48:49], v[38:41], off offset:1024
	v_add3_u32 v35, v83, v35, s42
	v_add3_u32 v37, v81, v37, s42
	v_add_f32_e32 v38, v57, v34
	v_and_b32_sdwa v34, v82, v117 dst_sel:DWORD dst_unused:UNUSED_PAD src0_sel:WORD_1 src1_sel:DWORD
	v_add3_u32 v34, v82, v34, s42
	v_and_b32_e32 v35, 0xffff0000, v35
	v_and_b32_e32 v37, 0xffff0000, v37
	v_or_b32_sdwa v35, v35, v34 dst_sel:DWORD dst_unused:UNUSED_PAD src0_sel:DWORD src1_sel:WORD_1
	v_or_b32_sdwa v34, v37, v36 dst_sel:DWORD dst_unused:UNUSED_PAD src0_sel:DWORD src1_sel:WORD_1
	v_and_b32_sdwa v37, v76, v117 dst_sel:DWORD dst_unused:UNUSED_PAD src0_sel:WORD_1 src1_sel:DWORD
	v_add3_u32 v39, v76, v37, s42
	v_and_b32_sdwa v37, v79, v117 dst_sel:DWORD dst_unused:UNUSED_PAD src0_sel:WORD_1 src1_sel:DWORD
	v_and_b32_sdwa v40, v77, v117 dst_sel:DWORD dst_unused:UNUSED_PAD src0_sel:WORD_1 src1_sel:DWORD
	v_and_b32_sdwa v36, v78, v117 dst_sel:DWORD dst_unused:UNUSED_PAD src0_sel:WORD_1 src1_sel:DWORD
	v_add3_u32 v37, v79, v37, s42
	v_add3_u32 v40, v77, v40, s42
	v_add3_u32 v36, v78, v36, s42
	v_and_b32_e32 v37, 0xffff0000, v37
	v_and_b32_e32 v40, 0xffff0000, v40
	v_or_b32_sdwa v37, v37, v36 dst_sel:DWORD dst_unused:UNUSED_PAD src0_sel:DWORD src1_sel:WORD_1
	v_or_b32_sdwa v36, v40, v39 dst_sel:DWORD dst_unused:UNUSED_PAD src0_sel:DWORD src1_sel:WORD_1
	global_store_dwordx4 v[48:49], v[34:37], off offset:2048
	s_waitcnt vmcnt(4)
	v_and_b32_sdwa v40, v85, v117 dst_sel:DWORD dst_unused:UNUSED_PAD src0_sel:WORD_1 src1_sel:DWORD
	v_add3_u32 v40, v85, v40, s42
	s_waitcnt vmcnt(3)
	v_mul_f32_e32 v34, v89, v89
	v_mul_f32_e32 v35, v91, v91
	v_fmac_f32_e32 v34, v88, v88
	v_fmac_f32_e32 v35, v90, v90
	v_add_f32_e32 v34, v34, v35
	v_mul_f32_e32 v35, v85, v85
	v_mul_f32_e32 v36, v87, v87
	v_fmac_f32_e32 v35, v84, v84
	v_fmac_f32_e32 v36, v86, v86
	v_add_f32_e32 v35, v35, v36
	v_add_f32_e32 v34, v34, v35
	v_and_b32_sdwa v35, v88, v117 dst_sel:DWORD dst_unused:UNUSED_PAD src0_sel:WORD_1 src1_sel:DWORD
	v_add3_u32 v36, v88, v35, s42
	v_and_b32_sdwa v35, v91, v117 dst_sel:DWORD dst_unused:UNUSED_PAD src0_sel:WORD_1 src1_sel:DWORD
	v_and_b32_sdwa v37, v89, v117 dst_sel:DWORD dst_unused:UNUSED_PAD src0_sel:WORD_1 src1_sel:DWORD
	v_add_f32_e32 v38, v38, v34
	v_and_b32_sdwa v34, v90, v117 dst_sel:DWORD dst_unused:UNUSED_PAD src0_sel:WORD_1 src1_sel:DWORD
	v_add3_u32 v35, v91, v35, s42
	v_add3_u32 v37, v89, v37, s42
	v_add3_u32 v34, v90, v34, s42
	v_and_b32_e32 v35, 0xffff0000, v35
	v_and_b32_e32 v37, 0xffff0000, v37
	v_or_b32_sdwa v35, v35, v34 dst_sel:DWORD dst_unused:UNUSED_PAD src0_sel:DWORD src1_sel:WORD_1
	v_or_b32_sdwa v34, v37, v36 dst_sel:DWORD dst_unused:UNUSED_PAD src0_sel:DWORD src1_sel:WORD_1
	v_and_b32_sdwa v37, v84, v117 dst_sel:DWORD dst_unused:UNUSED_PAD src0_sel:WORD_1 src1_sel:DWORD
	v_add3_u32 v39, v84, v37, s42
	v_and_b32_sdwa v37, v87, v117 dst_sel:DWORD dst_unused:UNUSED_PAD src0_sel:WORD_1 src1_sel:DWORD
	v_and_b32_sdwa v36, v86, v117 dst_sel:DWORD dst_unused:UNUSED_PAD src0_sel:WORD_1 src1_sel:DWORD
	v_add3_u32 v37, v87, v37, s42
	v_add3_u32 v36, v86, v36, s42
	v_and_b32_e32 v37, 0xffff0000, v37
	v_and_b32_e32 v40, 0xffff0000, v40
	v_or_b32_sdwa v37, v37, v36 dst_sel:DWORD dst_unused:UNUSED_PAD src0_sel:DWORD src1_sel:WORD_1
	v_or_b32_sdwa v36, v40, v39 dst_sel:DWORD dst_unused:UNUSED_PAD src0_sel:DWORD src1_sel:WORD_1
	global_store_dwordx4 v[48:49], v[34:37], off offset:3072
	s_nop 1
	v_mul_f32_e32 v34, v31, v31
	v_mul_f32_e32 v35, v33, v33
	v_fmac_f32_e32 v34, v30, v30
	v_fmac_f32_e32 v35, v32, v32
	v_add_f32_e32 v34, v34, v35
	v_mul_f32_e32 v35, v27, v27
	v_mul_f32_e32 v36, v29, v29
	v_fmac_f32_e32 v35, v26, v26
	v_fmac_f32_e32 v36, v28, v28
	v_add_f32_e32 v35, v35, v36
	v_add_f32_e32 v34, v34, v35
	v_and_b32_sdwa v35, v32, v117 dst_sel:DWORD dst_unused:UNUSED_PAD src0_sel:WORD_1 src1_sel:DWORD
	v_and_b32_sdwa v36, v30, v117 dst_sel:DWORD dst_unused:UNUSED_PAD src0_sel:WORD_1 src1_sel:DWORD
	v_add3_u32 v32, v32, v35, s42
	v_and_b32_sdwa v35, v33, v117 dst_sel:DWORD dst_unused:UNUSED_PAD src0_sel:WORD_1 src1_sel:DWORD
	v_add3_u32 v30, v30, v36, s42
	v_and_b32_sdwa v36, v31, v117 dst_sel:DWORD dst_unused:UNUSED_PAD src0_sel:WORD_1 src1_sel:DWORD
	v_add3_u32 v33, v33, v35, s42
	v_add3_u32 v31, v31, v36, s42
	v_and_b32_e32 v33, 0xffff0000, v33
	v_and_b32_e32 v35, 0xffff0000, v31
	v_or_b32_sdwa v31, v33, v32 dst_sel:DWORD dst_unused:UNUSED_PAD src0_sel:DWORD src1_sel:WORD_1
	v_and_b32_sdwa v33, v26, v117 dst_sel:DWORD dst_unused:UNUSED_PAD src0_sel:WORD_1 src1_sel:DWORD
	v_add3_u32 v26, v26, v33, s42
	v_and_b32_sdwa v33, v27, v117 dst_sel:DWORD dst_unused:UNUSED_PAD src0_sel:WORD_1 src1_sel:DWORD
	v_and_b32_sdwa v32, v28, v117 dst_sel:DWORD dst_unused:UNUSED_PAD src0_sel:WORD_1 src1_sel:DWORD
	v_add3_u32 v27, v27, v33, s42
; #define GAS __attribute__((address_space(1)))
; __device__ __forceinline__ unsigned pk2(float lo, float hi) { return f2bf(lo) | (f2bf(hi) << 16); }
; __device__ __forceinline__ float shx(float v, int o, int lane) { return __int_as_float(__builtin_amdgcn_ds_bpermute((lane ^ o) << 2, __float_as_int(v))); }
; __device__ __forceinline__ float dot4(f32x4 a) { return (a.x * a.x + a.y * a.y) + (a.z * a.z + a.w * a.w); }
; __device__ __forceinline__ float wave_sum(float v, int lane) {
; #pragma unroll
;     for (int o = 1; o < 64; o <<= 1) v += shx(v, o, lane);
;     return v;
; template <bool QUANT>
; __device__ __forceinline__ void cast_row(const float* __restrict__ xrow, bf16* __restrict__ xbrow, float* rs_out, int lane, signed char* xqrow = nullptr, float* rf_out = nullptr) {
;     ...
;     for (int j = 0; j < 8; ++j) { s += dot4(x[j][0]) + dot4(x[j][1]);
;         if (QUANT) {
; #pragma unroll
;             for (int e = 0; e < 4; ++e) am = fmaxf(am, fmaxf(fabsf(x[j][0][e]), fabsf(x[j][1][e]))); }
;         else { v4u w; w.x = pk2(x[j][0].x, x[j][0].y); w.y = pk2(x[j][0].z, x[j][0].w); w.z = pk2(x[j][1].x, x[j][1].y); w.w = pk2(x[j][1].z, x[j][1].w);
;             *(GAS v4u*)(xbrow + 8 * lane + 512 * j) = w; } }
;     const float tot = wave_sum(s, lane); const float rsn = 1.0f / sqrtf(tot * (1.0f / DM) + EPS);
	v_add3_u32 v28, v28, v32, s42
	v_and_b32_sdwa v32, v29, v117 dst_sel:DWORD dst_unused:UNUSED_PAD src0_sel:WORD_1 src1_sel:DWORD
	v_and_b32_e32 v27, 0xffff0000, v27
	v_add3_u32 v29, v29, v32, s42
	v_or_b32_sdwa v32, v27, v26 dst_sel:DWORD dst_unused:UNUSED_PAD src0_sel:DWORD src1_sel:WORD_1
	v_mul_f32_e32 v26, v23, v23
	v_mul_f32_e32 v27, v25, v25
	v_and_b32_e32 v29, 0xffff0000, v29
	v_fmac_f32_e32 v26, v22, v22
	v_fmac_f32_e32 v27, v24, v24
	v_or_b32_sdwa v33, v29, v28 dst_sel:DWORD dst_unused:UNUSED_PAD src0_sel:DWORD src1_sel:WORD_1
	v_add_f32_e32 v26, v26, v27
	v_mul_f32_e32 v27, v19, v19
	v_mul_f32_e32 v28, v21, v21
	v_fmac_f32_e32 v27, v18, v18
	v_fmac_f32_e32 v28, v20, v20
	v_add_f32_e32 v27, v27, v28
	v_add_f32_e32 v26, v26, v27
	v_and_b32_sdwa v27, v24, v117 dst_sel:DWORD dst_unused:UNUSED_PAD src0_sel:WORD_1 src1_sel:DWORD
	v_and_b32_sdwa v28, v22, v117 dst_sel:DWORD dst_unused:UNUSED_PAD src0_sel:WORD_1 src1_sel:DWORD
	v_add3_u32 v24, v24, v27, s42
	v_and_b32_sdwa v27, v25, v117 dst_sel:DWORD dst_unused:UNUSED_PAD src0_sel:WORD_1 src1_sel:DWORD
	v_add3_u32 v22, v22, v28, s42
	v_and_b32_sdwa v28, v23, v117 dst_sel:DWORD dst_unused:UNUSED_PAD src0_sel:WORD_1 src1_sel:DWORD
	v_add3_u32 v25, v25, v27, s42
	v_add3_u32 v23, v23, v28, s42
	v_and_b32_e32 v25, 0xffff0000, v25
	v_and_b32_e32 v27, 0xffff0000, v23
	v_or_b32_sdwa v23, v25, v24 dst_sel:DWORD dst_unused:UNUSED_PAD src0_sel:DWORD src1_sel:WORD_1
	v_and_b32_sdwa v25, v18, v117 dst_sel:DWORD dst_unused:UNUSED_PAD src0_sel:WORD_1 src1_sel:DWORD
	v_add3_u32 v18, v18, v25, s42
	v_and_b32_sdwa v25, v19, v117 dst_sel:DWORD dst_unused:UNUSED_PAD src0_sel:WORD_1 src1_sel:DWORD
	v_and_b32_sdwa v24, v20, v117 dst_sel:DWORD dst_unused:UNUSED_PAD src0_sel:WORD_1 src1_sel:DWORD
	v_add3_u32 v19, v19, v25, s42
	v_add3_u32 v20, v20, v24, s42
	v_and_b32_sdwa v24, v21, v117 dst_sel:DWORD dst_unused:UNUSED_PAD src0_sel:WORD_1 src1_sel:DWORD
	v_and_b32_e32 v19, 0xffff0000, v19
	v_add3_u32 v21, v21, v24, s42
	v_or_b32_sdwa v24, v19, v18 dst_sel:DWORD dst_unused:UNUSED_PAD src0_sel:DWORD src1_sel:WORD_1
	v_mul_f32_e32 v18, v15, v15
	v_mul_f32_e32 v19, v17, v17
	v_and_b32_e32 v21, 0xffff0000, v21
	v_fmac_f32_e32 v18, v14, v14
	v_fmac_f32_e32 v19, v16, v16
	v_or_b32_sdwa v25, v21, v20 dst_sel:DWORD dst_unused:UNUSED_PAD src0_sel:DWORD src1_sel:WORD_1
	v_add_f32_e32 v18, v18, v19
	v_mul_f32_e32 v19, v11, v11
	v_mul_f32_e32 v20, v13, v13
	v_fmac_f32_e32 v19, v10, v10
	v_fmac_f32_e32 v20, v12, v12
	v_add_f32_e32 v19, v19, v20
	v_add_f32_e32 v18, v18, v19
	v_and_b32_sdwa v19, v16, v117 dst_sel:DWORD dst_unused:UNUSED_PAD src0_sel:WORD_1 src1_sel:DWORD
	v_and_b32_sdwa v20, v14, v117 dst_sel:DWORD dst_unused:UNUSED_PAD src0_sel:WORD_1 src1_sel:DWORD
	v_add3_u32 v16, v16, v19, s42
	v_and_b32_sdwa v19, v17, v117 dst_sel:DWORD dst_unused:UNUSED_PAD src0_sel:WORD_1 src1_sel:DWORD
	v_add3_u32 v14, v14, v20, s42
	v_and_b32_sdwa v20, v15, v117 dst_sel:DWORD dst_unused:UNUSED_PAD src0_sel:WORD_1 src1_sel:DWORD
	v_add3_u32 v17, v17, v19, s42
	v_add3_u32 v15, v15, v20, s42
	v_and_b32_e32 v17, 0xffff0000, v17
	v_and_b32_e32 v19, 0xffff0000, v15
	v_or_b32_sdwa v15, v17, v16 dst_sel:DWORD dst_unused:UNUSED_PAD src0_sel:DWORD src1_sel:WORD_1
	v_and_b32_sdwa v17, v10, v117 dst_sel:DWORD dst_unused:UNUSED_PAD src0_sel:WORD_1 src1_sel:DWORD
	v_add3_u32 v10, v10, v17, s42
	v_and_b32_sdwa v17, v11, v117 dst_sel:DWORD dst_unused:UNUSED_PAD src0_sel:WORD_1 src1_sel:DWORD
	v_and_b32_sdwa v16, v12, v117 dst_sel:DWORD dst_unused:UNUSED_PAD src0_sel:WORD_1 src1_sel:DWORD
	v_add3_u32 v11, v11, v17, s42
	v_add3_u32 v12, v12, v16, s42
	v_and_b32_sdwa v16, v13, v117 dst_sel:DWORD dst_unused:UNUSED_PAD src0_sel:WORD_1 src1_sel:DWORD
	v_and_b32_e32 v11, 0xffff0000, v11
	v_add3_u32 v13, v13, v16, s42
	v_or_b32_sdwa v16, v11, v10 dst_sel:DWORD dst_unused:UNUSED_PAD src0_sel:DWORD src1_sel:WORD_1
	v_mul_f32_e32 v10, v7, v7
	v_mul_f32_e32 v11, v9, v9
	v_and_b32_e32 v13, 0xffff0000, v13
	v_fmac_f32_e32 v10, v6, v6
	v_fmac_f32_e32 v11, v8, v8
	v_or_b32_sdwa v17, v13, v12 dst_sel:DWORD dst_unused:UNUSED_PAD src0_sel:DWORD src1_sel:WORD_1
	v_add_f32_e32 v10, v10, v11
	v_mul_f32_e32 v11, v3, v3
	v_mul_f32_e32 v12, v5, v5
	v_add_f32_e32 v34, v38, v34
	v_fmac_f32_e32 v11, v2, v2
	v_fmac_f32_e32 v12, v4, v4
	v_add_f32_e32 v26, v34, v26
	v_add_f32_e32 v11, v11, v12
	v_add_f32_e32 v18, v26, v18
	v_add_f32_e32 v10, v10, v11
	v_add_f32_e32 v10, v18, v10
	ds_bpermute_b32 v12, v51, v10
	v_and_b32_sdwa v11, v8, v117 dst_sel:DWORD dst_unused:UNUSED_PAD src0_sel:WORD_1 src1_sel:DWORD
	v_add3_u32 v8, v8, v11, s42
	v_and_b32_sdwa v11, v9, v117 dst_sel:DWORD dst_unused:UNUSED_PAD src0_sel:WORD_1 src1_sel:DWORD
	v_add3_u32 v9, v9, v11, s42
	s_waitcnt lgkmcnt(0)
	v_add_f32_e32 v10, v10, v12
	ds_bpermute_b32 v12, v52, v10
	v_and_b32_sdwa v13, v6, v117 dst_sel:DWORD dst_unused:UNUSED_PAD src0_sel:WORD_1 src1_sel:DWORD
	v_add3_u32 v6, v6, v13, s42
	v_and_b32_sdwa v13, v7, v117 dst_sel:DWORD dst_unused:UNUSED_PAD src0_sel:WORD_1 src1_sel:DWORD
	v_add3_u32 v7, v7, v13, s42
	s_waitcnt lgkmcnt(0)
	v_add_f32_e32 v10, v10, v12
	ds_bpermute_b32 v11, v53, v10
	v_and_b32_e32 v9, 0xffff0000, v9
	v_and_b32_e32 v12, 0xffff0000, v7
	v_or_b32_sdwa v7, v9, v8 dst_sel:DWORD dst_unused:UNUSED_PAD src0_sel:DWORD src1_sel:WORD_1
	v_and_b32_sdwa v8, v4, v117 dst_sel:DWORD dst_unused:UNUSED_PAD src0_sel:WORD_1 src1_sel:DWORD
	s_waitcnt lgkmcnt(0)
	v_add_f32_e32 v9, v10, v11
	ds_bpermute_b32 v10, v54, v9
	v_add3_u32 v4, v4, v8, s42
	v_and_b32_sdwa v11, v2, v117 dst_sel:DWORD dst_unused:UNUSED_PAD src0_sel:WORD_1 src1_sel:DWORD
	v_add3_u32 v11, v2, v11, s42
	v_and_b32_sdwa v2, v5, v117 dst_sel:DWORD dst_unused:UNUSED_PAD src0_sel:WORD_1 src1_sel:DWORD
	s_waitcnt lgkmcnt(0)
	v_add_f32_e32 v8, v9, v10
	ds_bpermute_b32 v9, v55, v8
	v_and_b32_sdwa v10, v3, v117 dst_sel:DWORD dst_unused:UNUSED_PAD src0_sel:WORD_1 src1_sel:DWORD
	v_add3_u32 v2, v5, v2, s42
	v_add3_u32 v5, v3, v10, s42
	v_and_b32_e32 v10, 0xffff0000, v2
	s_waitcnt lgkmcnt(0)
	v_add_f32_e32 v2, v8, v9
	ds_bpermute_b32 v3, v56, v2
	v_and_b32_e32 v5, 0xffff0000, v5
	v_or_b32_sdwa v30, v35, v30 dst_sel:DWORD dst_unused:UNUSED_PAD src0_sel:DWORD src1_sel:WORD_1
	v_or_b32_sdwa v22, v27, v22 dst_sel:DWORD dst_unused:UNUSED_PAD src0_sel:DWORD src1_sel:WORD_1
	v_or_b32_sdwa v14, v19, v14 dst_sel:DWORD dst_unused:UNUSED_PAD src0_sel:DWORD src1_sel:WORD_1
	v_or_b32_sdwa v6, v12, v6 dst_sel:DWORD dst_unused:UNUSED_PAD src0_sel:DWORD src1_sel:WORD_1
	v_or_b32_sdwa v9, v10, v4 dst_sel:DWORD dst_unused:UNUSED_PAD src0_sel:DWORD src1_sel:WORD_1
	v_or_b32_sdwa v8, v5, v11 dst_sel:DWORD dst_unused:UNUSED_PAD src0_sel:DWORD src1_sel:WORD_1
	global_store_dwordx4 v[46:47], v[30:33], off
	global_store_dwordx4 v[46:47], v[22:25], off offset:1024
	global_store_dwordx4 v[46:47], v[14:17], off offset:2048
	global_store_dwordx4 v[46:47], v[6:9], off offset:3072
	s_and_saveexec_b64 s[36:37], s[46:47]
	s_cbranch_execz .LBB0_79
; template <bool QUANT>
; __device__ __forceinline__ void cast_row(const float* __restrict__ xrow, bf16* __restrict__ xbrow, float* rs_out, int lane, signed char* xqrow = nullptr, float* rf_out = nullptr) {
;     ...
;     const float tot = wave_sum(s, lane); const float rsn = 1.0f / sqrtf(tot * (1.0f / DM) + EPS);
;     if (lane == 0) *rs_out = rsn;
	s_waitcnt lgkmcnt(0)
	v_add_f32_e32 v2, v2, v3
	v_fmamk_f32 v2, v2, 0x39800000, v1
	s_mov_b32 s14, 0xf800000
	v_mul_f32_e32 v3, 0x4f800000, v2
	v_cmp_gt_f32_e32 vcc, s14, v2
	s_nop 1
	v_cndmask_b32_e32 v2, v2, v3, vcc
	v_sqrt_f32_e32 v3, v2
	s_nop 0
	v_add_u32_e32 v4, -1, v3
	v_add_u32_e32 v5, 1, v3
	v_fma_f32 v6, -v4, v3, v2
	v_fma_f32 v7, -v5, v3, v2
	v_cmp_ge_f32_e64 s[48:49], 0, v6
	s_nop 1
	v_cndmask_b32_e64 v3, v3, v4, s[48:49]
	v_cmp_lt_f32_e64 s[48:49], 0, v7
	s_nop 1
	v_cndmask_b32_e64 v3, v3, v5, s[48:49]
	v_mul_f32_e32 v4, 0x37800000, v3
	v_cndmask_b32_e32 v3, v3, v4, vcc
	v_cmp_class_f32_e32 vcc, v2, v115
	s_nop 1
	v_cndmask_b32_e32 v2, v3, v2, vcc
	v_div_scale_f32 v3, s[14:15], v2, v2, 1.0
	v_rcp_f32_e32 v4, v3
	s_add_u32 s14, s12, s18
	s_addc_u32 s15, s13, s19
	v_fma_f32 v5, -v3, v4, 1.0
	v_fmac_f32_e32 v4, v5, v4
	v_div_scale_f32 v5, vcc, 1.0, v2, 1.0
	v_mul_f32_e32 v6, v5, v4
	v_fma_f32 v7, -v3, v6, v5
	v_fmac_f32_e32 v6, v7, v4
	v_fma_f32 v3, -v3, v6, v5
	v_div_fmas_f32 v3, v3, v4, v6
	v_div_fixup_f32 v2, v3, v2, 1.0
	global_store_dword v67, v2, s[14:15]
	s_branch .LBB0_79
